# adds hand-written head-norm statistics path for the XQ/KV GEMM epilogue (same technique as QKV)
# baseline (speedup 1.0000x reference)
; __device__ __forceinline__ float shx(float v, int lane, int mask) { return __builtin_bit_cast(float, __builtin_amdgcn_ds_bpermute((lane ^ mask) << 2, __builtin_bit_cast(int, v))); }
; #define PG8_XBAR() do { asm volatile("s_waitcnt lgkmcnt(0)" ::: "memory"); __builtin_amdgcn_s_barrier(); asm volatile("" ::: "memory"); } while (0)
;     __device__ __forceinline__ void operator()(AccT& acc, const Unit& u, int wr, int wc, int fr, int fq, PG8_LAS unsigned char* lds) const {
;     ...
;                 for (int m = 0; m < 4; ++m) { float s[2];
; #pragma unroll
;                     for (int bj = 0; bj < 2; ++bj) { const f32x4 a = acc[ai][bj][m][0], b = acc[ai][bj][m][1];
;                         s[bj] = ((a.x * a.x + a.y * a.y) + (a.z * a.z + a.w * a.w)) + ((b.x * b.x + b.y * b.y) + (b.z * b.z + b.w * b.w)); }
;                     if (NSEG == 1) { s[0] += s[1]; s[1] = 0.f; }
; #pragma unroll
;                     for (int sg = 0; sg < NSEG; ++sg) { float t = s[sg]; t += shx(t, fr + 16 * fq, 16); t += shx(t, fr + 16 * fq, 32);
;                         if (fq == 0) P[((ai * HALF + wr * 64 + m * 16 + fr) * 2 + sg) * 4 + wc] = t; } }
;             PG8_XBAR();
.LBB0_401:
	v_pk_mul_f32 v[190:191], v[124:125], v[124:125]
	v_pk_fma_f32 v[190:191], v[126:127], v[126:127], v[190:191]
	v_pk_fma_f32 v[190:191], v[120:121], v[120:121], v[190:191]
	v_pk_fma_f32 v[190:191], v[122:123], v[122:123], v[190:191]
	v_pk_fma_f32 v[190:191], v[116:117], v[116:117], v[190:191]
	v_pk_fma_f32 v[190:191], v[118:119], v[118:119], v[190:191]
	v_pk_fma_f32 v[190:191], v[112:113], v[112:113], v[190:191]
	v_pk_fma_f32 v[190:191], v[114:115], v[114:115], v[190:191]
	v_add_f32_e32 v182, v190, v191
	v_pk_mul_f32 v[192:193], v[108:109], v[108:109]
	v_pk_fma_f32 v[192:193], v[110:111], v[110:111], v[192:193]
	v_pk_fma_f32 v[192:193], v[104:105], v[104:105], v[192:193]
	v_pk_fma_f32 v[192:193], v[106:107], v[106:107], v[192:193]
	v_pk_fma_f32 v[192:193], v[100:101], v[100:101], v[192:193]
	v_pk_fma_f32 v[192:193], v[102:103], v[102:103], v[192:193]
	v_pk_fma_f32 v[192:193], v[96:97], v[96:97], v[192:193]
	v_pk_fma_f32 v[192:193], v[98:99], v[98:99], v[192:193]
	v_add_f32_e32 v183, v192, v193
	v_pk_mul_f32 v[190:191], v[92:93], v[92:93]
	v_pk_fma_f32 v[190:191], v[94:95], v[94:95], v[190:191]
	v_pk_fma_f32 v[190:191], v[88:89], v[88:89], v[190:191]
	v_pk_fma_f32 v[190:191], v[90:91], v[90:91], v[190:191]
	v_pk_fma_f32 v[190:191], v[84:85], v[84:85], v[190:191]
	v_pk_fma_f32 v[190:191], v[86:87], v[86:87], v[190:191]
	v_pk_fma_f32 v[190:191], v[80:81], v[80:81], v[190:191]
	v_pk_fma_f32 v[190:191], v[82:83], v[82:83], v[190:191]
	v_add_f32_e32 v184, v190, v191
	v_pk_mul_f32 v[192:193], v[76:77], v[76:77]
	v_pk_fma_f32 v[192:193], v[78:79], v[78:79], v[192:193]
	v_pk_fma_f32 v[192:193], v[72:73], v[72:73], v[192:193]
	v_pk_fma_f32 v[192:193], v[74:75], v[74:75], v[192:193]
	v_pk_fma_f32 v[192:193], v[68:69], v[68:69], v[192:193]
	v_pk_fma_f32 v[192:193], v[70:71], v[70:71], v[192:193]
	v_pk_fma_f32 v[192:193], v[64:65], v[64:65], v[192:193]
	v_pk_fma_f32 v[192:193], v[66:67], v[66:67], v[192:193]
	v_add_f32_e32 v185, v192, v193
	v_pk_mul_f32 v[190:191], v[60:61], v[60:61]
	v_pk_fma_f32 v[190:191], v[62:63], v[62:63], v[190:191]
	v_pk_fma_f32 v[190:191], v[56:57], v[56:57], v[190:191]
	v_pk_fma_f32 v[190:191], v[58:59], v[58:59], v[190:191]
	v_pk_fma_f32 v[190:191], v[52:53], v[52:53], v[190:191]
	v_pk_fma_f32 v[190:191], v[54:55], v[54:55], v[190:191]
	v_pk_fma_f32 v[190:191], v[48:49], v[48:49], v[190:191]
	v_pk_fma_f32 v[190:191], v[50:51], v[50:51], v[190:191]
	v_add_f32_e32 v186, v190, v191
	v_pk_mul_f32 v[192:193], v[44:45], v[44:45]
	v_pk_fma_f32 v[192:193], v[46:47], v[46:47], v[192:193]
	v_pk_fma_f32 v[192:193], v[40:41], v[40:41], v[192:193]
	v_pk_fma_f32 v[192:193], v[42:43], v[42:43], v[192:193]
	v_pk_fma_f32 v[192:193], v[36:37], v[36:37], v[192:193]
	v_pk_fma_f32 v[192:193], v[38:39], v[38:39], v[192:193]
	v_pk_fma_f32 v[192:193], v[32:33], v[32:33], v[192:193]
	v_pk_fma_f32 v[192:193], v[34:35], v[34:35], v[192:193]
	v_add_f32_e32 v187, v192, v193
	v_pk_mul_f32 v[190:191], v[28:29], v[28:29]
	v_pk_fma_f32 v[190:191], v[30:31], v[30:31], v[190:191]
	v_pk_fma_f32 v[190:191], v[24:25], v[24:25], v[190:191]
	v_pk_fma_f32 v[190:191], v[26:27], v[26:27], v[190:191]
	v_pk_fma_f32 v[190:191], v[20:21], v[20:21], v[190:191]
	v_pk_fma_f32 v[190:191], v[22:23], v[22:23], v[190:191]
	v_pk_fma_f32 v[190:191], v[16:17], v[16:17], v[190:191]
	v_pk_fma_f32 v[190:191], v[18:19], v[18:19], v[190:191]
	v_add_f32_e32 v188, v190, v191
	v_pk_mul_f32 v[192:193], v[12:13], v[12:13]
	v_pk_fma_f32 v[192:193], v[14:15], v[14:15], v[192:193]
	v_pk_fma_f32 v[192:193], v[8:9], v[8:9], v[192:193]
	v_pk_fma_f32 v[192:193], v[10:11], v[10:11], v[192:193]
	v_pk_fma_f32 v[192:193], v[4:5], v[4:5], v[192:193]
	v_pk_fma_f32 v[192:193], v[6:7], v[6:7], v[192:193]
	v_pk_fma_f32 v[192:193], v[0:1], v[0:1], v[192:193]
	v_pk_fma_f32 v[192:193], v[2:3], v[2:3], v[192:193]
	v_add_f32_e32 v189, v192, v193
	v_mbcnt_lo_u32_b32 v168, -1, 0
	v_mbcnt_hi_u32_b32 v168, -1, v168
	v_and_b32_e32 v168, 48, v168
	v_lshlrev_b32_e32 v168, 5, v168
	v_add3_u32 v194, v177, v168, s64
	v_permlane16_swap_b32_e32 v182, v183
	v_permlane16_swap_b32_e32 v184, v185
	v_permlane16_swap_b32_e32 v186, v187
	v_permlane16_swap_b32_e32 v188, v189
	v_add_f32_e32 v182, v182, v183
	v_add_f32_e32 v184, v184, v185
	v_add_f32_e32 v186, v186, v187
	v_add_f32_e32 v188, v188, v189
	s_nop 0
	v_permlane32_swap_b32_e32 v182, v184
	v_permlane32_swap_b32_e32 v186, v188
	v_add_f32_e32 v182, v182, v184
	v_add_f32_e32 v186, v186, v188
	ds_write_b32 v194, v182
	ds_write_b32 v194, v186 offset:4096
	s_waitcnt vmcnt(0) lgkmcnt(0)
	s_barrier
; #define PG8_LAS __attribute__((address_space(3)))
;     __device__ __forceinline__ void operator()(AccT& acc, const Unit& u, int wr, int wc, int fr, int fq, PG8_LAS unsigned char* lds) const {
;     ...
; #pragma unroll
;             for (int ai = 0; ai < 2; ++ai)
; #pragma unroll
;                 for (int m = 0; m < 4; ++m)
; #pragma unroll
;                     for (int sg = 0; sg < NSEG; ++sg) { const f32x4 t = *(const PG8_LAS f32x4*)(P + ((ai * HALF + wr * 64 + m * 16 + fr) * 2 + sg) * 4);
;                         const float r0 = rs[ai][m]; rn[ai][m][sg] = rsqrtf(((t.x + t.y) + (t.z + t.w)) * (r0 * r0) * (NSEG == 1 ? 1.0f / 256.f : 1.0f / 128.f) + 1e-6f) * (psc * r0); }
	v_add_u32_e32 v194, 0x20000, v177
	ds_read_b128 v[182:185], v194
	ds_read_b128 v[186:189], v194 offset:512
	ds_read_b128 v[190:193], v194 offset:1024
	s_waitcnt lgkmcnt(2)
	v_mul_f32_e32 v168, v166, v166
	v_mul_f32_e32 v169, s2, v166
	v_mul_f32_e32 v168, 0x3b800000, v168
	v_pk_add_f32 v[182:183], v[182:183], v[184:185]
	s_nop 0
	v_add_f32_e32 v182, v182, v183
	v_fmaak_f32 v182, v182, v168, 0x358637bd
	v_rsq_f32_e32 v182, v182
	s_nop 0
	v_mul_f32_e32 v166, v182, v169
	ds_read_b128 v[182:185], v194 offset:1536
	s_waitcnt lgkmcnt(2)
	v_mul_f32_e32 v168, v167, v167
	v_mul_f32_e32 v169, s2, v167
	v_mul_f32_e32 v168, 0x3b800000, v168
	v_pk_add_f32 v[186:187], v[186:187], v[188:189]
	s_nop 0
	v_add_f32_e32 v186, v186, v187
	v_fmaak_f32 v186, v186, v168, 0x358637bd
	v_rsq_f32_e32 v186, v186
	s_nop 0
	v_mul_f32_e32 v167, v186, v169
	ds_read_b128 v[186:189], v194 offset:4096
	s_waitcnt lgkmcnt(2)
	v_mul_f32_e32 v168, v164, v164
	v_mul_f32_e32 v169, s2, v164
	v_mul_f32_e32 v168, 0x3b800000, v168
	v_pk_add_f32 v[190:191], v[190:191], v[192:193]
	s_nop 0
	v_add_f32_e32 v190, v190, v191
	v_fmaak_f32 v190, v190, v168, 0x358637bd
	v_rsq_f32_e32 v190, v190
	s_nop 0
	v_mul_f32_e32 v164, v190, v169
	ds_read_b128 v[190:193], v194 offset:4608
	s_waitcnt lgkmcnt(2)
	v_mul_f32_e32 v168, v165, v165
	v_mul_f32_e32 v169, s2, v165
	v_mul_f32_e32 v168, 0x3b800000, v168
	v_pk_add_f32 v[182:183], v[182:183], v[184:185]
	s_nop 0
	v_add_f32_e32 v182, v182, v183
	v_fmaak_f32 v182, v182, v168, 0x358637bd
	v_rsq_f32_e32 v182, v182
	s_nop 0
	v_mul_f32_e32 v165, v182, v169
	ds_read_b128 v[182:185], v194 offset:5120
	s_waitcnt lgkmcnt(2)
	v_mul_f32_e32 v168, v162, v162
	v_mul_f32_e32 v169, s2, v162
	v_mul_f32_e32 v168, 0x3b800000, v168
	v_pk_add_f32 v[186:187], v[186:187], v[188:189]
	s_nop 0
	v_add_f32_e32 v186, v186, v187
	v_fmaak_f32 v186, v186, v168, 0x358637bd
	v_rsq_f32_e32 v186, v186
	s_nop 0
	v_mul_f32_e32 v162, v186, v169
	ds_read_b128 v[186:189], v194 offset:5632
	s_waitcnt lgkmcnt(2)
	v_mul_f32_e32 v168, v163, v163
	v_mul_f32_e32 v169, s2, v163
	v_mul_f32_e32 v168, 0x3b800000, v168
	v_pk_add_f32 v[190:191], v[190:191], v[192:193]
	s_nop 0
	v_add_f32_e32 v190, v190, v191
	v_fmaak_f32 v190, v190, v168, 0x358637bd
	v_rsq_f32_e32 v190, v190
	s_nop 0
	v_mul_f32_e32 v163, v190, v169
	s_waitcnt lgkmcnt(1)
	v_mul_f32_e32 v168, v160, v160
	v_mul_f32_e32 v169, s2, v160
	v_mul_f32_e32 v168, 0x3b800000, v168
	v_pk_add_f32 v[182:183], v[182:183], v[184:185]
	s_nop 0
	v_add_f32_e32 v182, v182, v183
	v_fmaak_f32 v182, v182, v168, 0x358637bd
	v_rsq_f32_e32 v182, v182
	s_nop 0
	v_mul_f32_e32 v160, v182, v169
	s_waitcnt lgkmcnt(0)
	v_mul_f32_e32 v168, v161, v161
	v_mul_f32_e32 v169, s2, v161
	v_mul_f32_e32 v168, 0x3b800000, v168
	v_pk_add_f32 v[186:187], v[186:187], v[188:189]
	s_nop 0
	v_add_f32_e32 v186, v186, v187
	v_fmaak_f32 v186, v186, v168, 0x358637bd
	v_rsq_f32_e32 v186, v186
	s_nop 0
	v_mul_f32_e32 v161, v186, v169
